# k15 + MoBA gating: key-block means of (b,h) staged in the wave's LDS once per unit, 56 serialized global loads become ds_read_b128
# baseline (speedup 1.0000x reference)
.LBB0_1498:
	s_or_b64 exec, exec, s[0:1]
	v_readfirstlane_b32 s40, v0
	s_cmpk_gt_u32 s40, 0x7ff
	s_mov_b64 s[0:1], -1
	s_cbranch_scc1 .LBB0_1493
	s_xor_b32 s40, s40, 0x400
	v_mov_b32_e32 v188, v240
	s_cmpk_gt_u32 s40, 0x3ff
	v_ashrrev_i32_e32 v196, 5, v188
	s_cbranch_scc0 .LBB0_1565
	s_not_b32 s0, s40
	s_bfe_u32 s42, s0, 0x60002
	v_ashrrev_i32_e32 v189, 5, v188
	s_and_b32 s43, s40, 3
	s_lshl_b32 s41, s42, 5
	s_waitcnt vmcnt(15)
	v_lshlrev_b32_e32 v146, 3, v189
	s_cmpk_gt_u32 s40, 0x5ff
	v_and_or_b32 v190, v188, 31, s41
	v_ashrrev_i32_e32 v147, 31, v146
	s_mov_b64 s[0:1], -1
	s_cbranch_scc0 .LBB0_1541
	s_add_i32 s0, s40, 0xfffffa00
	s_lshr_b32 s0, s0, 6
	s_and_b32 s0, s0, 0x3fffffc
	v_readlane_b32 s1, v255, 1
	s_add_i32 s0, s0, s1
	s_or_b32 s36, s0, s43
	s_lshl_b32 s0, s0, 9
	s_and_b32 s0, s0, 0x7800
	v_or_b32_e32 v184, s0, v190
	v_readlane_b32 s0, v255, 6
	v_lshlrev_b32_e32 v0, 9, v184
	v_readlane_b32 s1, v255, 7
	s_mov_b32 s19, s37
	v_readlane_b32 s2, v255, 10
	v_lshl_add_u64 v[2:3], s[0:1], 0, v[0:1]
	s_lshl_b32 s0, s36, 6
	s_and_b32 s0, s0, 0xc0
	s_lshl_b32 s18, s0, 1
	v_lshl_add_u64 v[2:3], v[2:3], 0, s[18:19]
	v_lshl_add_u64 v[2:3], v[146:147], 1, v[2:3]
	global_load_dwordx4 v[66:69], v[2:3], off
	global_load_dwordx4 v[70:73], v[2:3], off offset:32
	global_load_dwordx4 v[74:77], v[2:3], off offset:64
	global_load_dwordx4 v[78:81], v[2:3], off offset:96
	s_lshl_b64 s[0:1], s[36:37], 11
	s_add_u32 s0, s2, s0
	v_readlane_b32 s2, v255, 11
	s_addc_u32 s1, s2, s1
	s_cmp_lt_u32 s42, 8
	v_lshl_add_u64 v[2:3], v[146:147], 2, s[0:1]
	s_cselect_b64 s[0:1], -1, 0
	v_mov_b32_e32 v0, 0
	v_mov_b32_e32 v16, 0
	s_and_b64 vcc, exec, s[0:1]
	s_waitcnt vmcnt(3)
	v_lshlrev_b32_e32 v29, 16, v66
	v_lshlrev_b32_e32 v30, 16, v68
	v_and_b32_e32 v31, 0xffff0000, v66
	v_and_b32_e32 v32, 0xffff0000, v68
	v_lshlrev_b32_e32 v33, 16, v67
	v_lshlrev_b32_e32 v34, 16, v69
	v_and_b32_e32 v35, 0xffff0000, v67
	v_and_b32_e32 v36, 0xffff0000, v69
	s_waitcnt vmcnt(2)
	v_lshlrev_b32_e32 v21, 16, v70
	v_lshlrev_b32_e32 v22, 16, v72
	v_and_b32_e32 v23, 0xffff0000, v70
	v_and_b32_e32 v24, 0xffff0000, v72
	v_lshlrev_b32_e32 v25, 16, v71
	v_lshlrev_b32_e32 v26, 16, v73
	v_and_b32_e32 v27, 0xffff0000, v71
	v_and_b32_e32 v28, 0xffff0000, v73
	s_waitcnt vmcnt(1)
	v_lshlrev_b32_e32 v17, 16, v74
	v_lshlrev_b32_e32 v18, 16, v76
	v_and_b32_e32 v19, 0xffff0000, v74
	v_and_b32_e32 v20, 0xffff0000, v76
	v_lshlrev_b32_e32 v15, 16, v75
	v_lshlrev_b32_e32 v14, 16, v77
	v_and_b32_e32 v13, 0xffff0000, v75
	v_and_b32_e32 v12, 0xffff0000, v77
	s_waitcnt vmcnt(0)
	v_lshlrev_b32_e32 v11, 16, v78
	v_lshlrev_b32_e32 v10, 16, v80
	v_and_b32_e32 v9, 0xffff0000, v78
	v_and_b32_e32 v8, 0xffff0000, v80
	v_lshlrev_b32_e32 v7, 16, v79
	v_lshlrev_b32_e32 v6, 16, v81
	v_and_b32_e32 v5, 0xffff0000, v79
	v_and_b32_e32 v4, 0xffff0000, v81
	v_lshlrev_b32_e32 v62, 4, v188
	v_lshrrev_b32_e32 v53, 5, v188
	v_lshlrev_b32_e32 v53, 5, v53
	v_sub_u32_e32 v62, v62, v53
	v_mov_b32_e32 v63, 0
	v_lshl_add_u64 v[64:65], v[2:3], 0, v[62:63]
	global_load_dwordx4 v[54:57], v[64:65], off
	global_load_dwordx4 v[58:61], v[64:65], off offset:1024
	v_readlane_b32 s2, v253, 16
	s_lshl_b32 s2, s2, 14
	s_nop 1
	v_lshl_add_u32 v62, v188, 4, s2
	v_add_u32_e32 v52, s2, v53
	s_waitcnt vmcnt(0)
	ds_write_b128 v62, v[54:57]
	ds_write_b128 v62, v[58:61] offset:1024
	s_waitcnt lgkmcnt(0)
	s_cbranch_vccnz .LBB0_1503
	ds_read_b128 v[38:41], v52 offset:16
	ds_read_b128 v[42:45], v52
	v_xor_b32_e32 v37, 32, v235
	s_waitcnt lgkmcnt(0)
	v_fma_f32 v16, v42, v29, 0
	v_fmac_f32_e32 v16, v38, v30
	v_fmac_f32_e32 v16, v43, v31
	v_fmac_f32_e32 v16, v39, v32
	v_fmac_f32_e32 v16, v44, v33
	v_fmac_f32_e32 v16, v40, v34
	v_fmac_f32_e32 v16, v45, v35
	v_fmac_f32_e32 v16, v41, v36
	ds_read_b128 v[38:41], v52 offset:80
	ds_read_b128 v[42:45], v52 offset:64
	s_waitcnt lgkmcnt(0)
	v_fmac_f32_e32 v16, v42, v21
	v_fmac_f32_e32 v16, v38, v22
	v_fmac_f32_e32 v16, v43, v23
	v_fmac_f32_e32 v16, v39, v24
	v_fmac_f32_e32 v16, v44, v25
	v_fmac_f32_e32 v16, v40, v26
	v_fmac_f32_e32 v16, v45, v27
	v_fmac_f32_e32 v16, v41, v28
	ds_read_b128 v[38:41], v52 offset:144
	ds_read_b128 v[42:45], v52 offset:128
	s_waitcnt lgkmcnt(0)
	v_fmac_f32_e32 v16, v42, v17
	v_fmac_f32_e32 v16, v38, v18
	v_fmac_f32_e32 v16, v43, v19
	v_fmac_f32_e32 v16, v39, v20
	v_mov_b32_e32 v38, v40
	v_mov_b32_e32 v39, v44
	v_pk_mul_f32 v[38:39], v[38:39], v[14:15]
	v_mov_b32_e32 v44, v41
	v_add_f32_e32 v16, v39, v16
	v_add_f32_e32 v16, v38, v16
	v_pk_mul_f32 v[38:39], v[44:45], v[12:13]
	s_nop 0
	v_add_f32_e32 v16, v39, v16
	v_add_f32_e32 v16, v38, v16
	ds_read_b128 v[38:41], v52 offset:208
	ds_read_b128 v[42:45], v52 offset:192
	s_waitcnt lgkmcnt(1)
	v_mov_b32_e32 v46, v38
	s_waitcnt lgkmcnt(0)
	v_mov_b32_e32 v47, v42
	v_pk_mul_f32 v[46:47], v[46:47], v[10:11]
	v_mov_b32_e32 v42, v39
	v_add_f32_e32 v16, v47, v16
	v_add_f32_e32 v16, v46, v16
	v_pk_mul_f32 v[38:39], v[42:43], v[8:9]
	s_nop 0
	v_add_f32_e32 v16, v39, v16
	v_add_f32_e32 v16, v38, v16
	v_mov_b32_e32 v38, v40
	v_mov_b32_e32 v39, v44
	v_pk_mul_f32 v[38:39], v[38:39], v[6:7]
	v_mov_b32_e32 v44, v41
	v_add_f32_e32 v16, v39, v16
	v_add_f32_e32 v16, v38, v16
	v_pk_mul_f32 v[38:39], v[44:45], v[4:5]
	s_nop 0
	v_add_f32_e32 v16, v39, v16
	v_add_f32_e32 v16, v38, v16
	v_and_b32_e32 v38, 64, v235
	v_add_u32_e32 v38, 64, v38
	v_cmp_lt_i32_e32 vcc, v37, v38
	s_nop 1
	v_cndmask_b32_e32 v37, v235, v37, vcc
	v_lshlrev_b32_e32 v37, 2, v37
	ds_bpermute_b32 v37, v37, v16
	s_waitcnt lgkmcnt(0)
	v_add_f32_e32 v16, v16, v37
.LBB0_1503:
	s_cmp_gt_u32 s42, 15
	s_cselect_b64 s[8:9], -1, 0
	s_cmp_lt_u32 s42, 16
	s_cbranch_scc1 .LBB0_1505
	ds_read_b128 v[38:41], v52 offset:272
	ds_read_b128 v[42:45], v52 offset:256
	v_xor_b32_e32 v37, 32, v235
	s_waitcnt lgkmcnt(0)
	v_fma_f32 v0, v42, v29, 0
	v_fmac_f32_e32 v0, v38, v30
	v_fmac_f32_e32 v0, v43, v31
	v_fmac_f32_e32 v0, v39, v32
	v_fmac_f32_e32 v0, v44, v33
	v_fmac_f32_e32 v0, v40, v34
	v_fmac_f32_e32 v0, v45, v35
	v_fmac_f32_e32 v0, v41, v36
	ds_read_b128 v[38:41], v52 offset:336
	ds_read_b128 v[42:45], v52 offset:320
	s_waitcnt lgkmcnt(0)
	v_fmac_f32_e32 v0, v42, v21
	v_fmac_f32_e32 v0, v38, v22
	v_fmac_f32_e32 v0, v43, v23
	v_fmac_f32_e32 v0, v39, v24
	v_fmac_f32_e32 v0, v44, v25
	v_fmac_f32_e32 v0, v40, v26
	v_fmac_f32_e32 v0, v45, v27
	v_fmac_f32_e32 v0, v41, v28
	ds_read_b128 v[38:41], v52 offset:400
	ds_read_b128 v[42:45], v52 offset:384
	s_waitcnt lgkmcnt(0)
	v_fmac_f32_e32 v0, v42, v17
	v_fmac_f32_e32 v0, v38, v18
	v_fmac_f32_e32 v0, v43, v19
	v_fmac_f32_e32 v0, v39, v20
	v_mov_b32_e32 v38, v40
	v_mov_b32_e32 v39, v44
	v_pk_mul_f32 v[38:39], v[38:39], v[14:15]
	v_mov_b32_e32 v44, v41
	v_add_f32_e32 v0, v39, v0
	v_add_f32_e32 v0, v38, v0
	v_pk_mul_f32 v[38:39], v[44:45], v[12:13]
	s_nop 0
	v_add_f32_e32 v0, v39, v0
	v_add_f32_e32 v0, v38, v0
	ds_read_b128 v[38:41], v52 offset:464
	ds_read_b128 v[42:45], v52 offset:448
	s_waitcnt lgkmcnt(1)
	v_mov_b32_e32 v46, v38
	s_waitcnt lgkmcnt(0)
	v_mov_b32_e32 v47, v42
	v_pk_mul_f32 v[46:47], v[46:47], v[10:11]
	v_mov_b32_e32 v42, v39
	v_add_f32_e32 v0, v47, v0
	v_add_f32_e32 v0, v46, v0
	v_pk_mul_f32 v[38:39], v[42:43], v[8:9]
	s_nop 0
	v_add_f32_e32 v0, v39, v0
	v_add_f32_e32 v0, v38, v0
	v_mov_b32_e32 v38, v40
	v_mov_b32_e32 v39, v44
	v_pk_mul_f32 v[38:39], v[38:39], v[6:7]
	v_mov_b32_e32 v44, v41
	v_add_f32_e32 v0, v39, v0
	v_add_f32_e32 v0, v38, v0
	v_pk_mul_f32 v[38:39], v[44:45], v[4:5]
	s_nop 0
	v_add_f32_e32 v0, v39, v0
	v_add_f32_e32 v0, v38, v0
	v_and_b32_e32 v38, 64, v235
	v_add_u32_e32 v38, 64, v38
	v_cmp_lt_i32_e32 vcc, v37, v38
	s_nop 1
	v_cndmask_b32_e32 v37, v235, v37, vcc
	v_lshlrev_b32_e32 v37, 2, v37
	ds_bpermute_b32 v37, v37, v0
	s_waitcnt lgkmcnt(0)
	v_add_f32_e32 v0, v0, v37
.LBB0_1505:
	s_cmp_gt_u32 s42, 23
	v_mov_b32_e32 v37, 0
	s_cselect_b64 s[20:21], -1, 0
	s_cmp_lt_u32 s42, 24
	v_mov_b32_e32 v38, 0
	s_cbranch_scc1 .LBB0_1507
	ds_read_b128 v[38:41], v52 offset:528
	ds_read_b128 v[42:45], v52 offset:512
	s_waitcnt lgkmcnt(0)
	v_fma_f32 v46, v42, v29, 0
	v_fmac_f32_e32 v46, v38, v30
	v_fmac_f32_e32 v46, v43, v31
	v_fmac_f32_e32 v46, v39, v32
	v_fmac_f32_e32 v46, v44, v33
	v_fmac_f32_e32 v46, v40, v34
	v_fmac_f32_e32 v46, v45, v35
	v_fmac_f32_e32 v46, v41, v36
	ds_read_b128 v[38:41], v52 offset:592
	ds_read_b128 v[42:45], v52 offset:576
	s_waitcnt lgkmcnt(0)
	v_fmac_f32_e32 v46, v42, v21
	v_fmac_f32_e32 v46, v38, v22
	v_fmac_f32_e32 v46, v43, v23
	v_fmac_f32_e32 v46, v39, v24
	v_fmac_f32_e32 v46, v44, v25
	v_fmac_f32_e32 v46, v40, v26
	v_fmac_f32_e32 v46, v45, v27
	v_fmac_f32_e32 v46, v41, v28
	ds_read_b128 v[38:41], v52 offset:656
	ds_read_b128 v[42:45], v52 offset:640
	s_waitcnt lgkmcnt(0)
	v_fmac_f32_e32 v46, v42, v17
	v_fmac_f32_e32 v46, v38, v18
	v_fmac_f32_e32 v46, v43, v19
	v_fmac_f32_e32 v46, v39, v20
	v_mov_b32_e32 v38, v40
	v_mov_b32_e32 v39, v44
	v_pk_mul_f32 v[38:39], v[38:39], v[14:15]
	v_mov_b32_e32 v44, v41
	v_add_f32_e32 v39, v39, v46
	v_add_f32_e32 v40, v38, v39
	v_pk_mul_f32 v[38:39], v[44:45], v[12:13]
	s_nop 0
	v_add_f32_e32 v39, v39, v40
	v_add_f32_e32 v48, v38, v39
	ds_read_b128 v[38:41], v52 offset:720
	ds_read_b128 v[42:45], v52 offset:704
	s_waitcnt lgkmcnt(1)
	v_mov_b32_e32 v46, v38
	s_waitcnt lgkmcnt(0)
	v_mov_b32_e32 v47, v42
	v_pk_mul_f32 v[46:47], v[46:47], v[10:11]
	v_mov_b32_e32 v42, v39
	v_add_f32_e32 v38, v47, v48
	v_add_f32_e32 v46, v46, v38
	v_pk_mul_f32 v[38:39], v[42:43], v[8:9]
	s_nop 0
	v_add_f32_e32 v39, v39, v46
	v_add_f32_e32 v42, v38, v39
	v_mov_b32_e32 v38, v40
	v_mov_b32_e32 v39, v44
	v_pk_mul_f32 v[38:39], v[38:39], v[6:7]
	v_mov_b32_e32 v44, v41
	v_add_f32_e32 v39, v39, v42
	v_add_f32_e32 v40, v38, v39
	v_pk_mul_f32 v[38:39], v[44:45], v[4:5]
	s_nop 0
	v_add_f32_e32 v39, v39, v40
	v_and_b32_e32 v40, 64, v235
	v_add_f32_e32 v38, v38, v39
	v_xor_b32_e32 v39, 32, v235
	v_add_u32_e32 v40, 64, v40
	v_cmp_lt_i32_e32 vcc, v39, v40
	s_nop 1
	v_cndmask_b32_e32 v39, v235, v39, vcc
	v_lshlrev_b32_e32 v39, 2, v39
	ds_bpermute_b32 v39, v39, v38
	s_waitcnt lgkmcnt(0)
	v_add_f32_e32 v38, v38, v39
.LBB0_1507:
	s_cmp_gt_u32 s42, 31
	s_cselect_b64 s[22:23], -1, 0
	s_cmp_lt_u32 s42, 32
	s_cbranch_scc1 .LBB0_1509
	ds_read_b128 v[40:43], v52 offset:784
	ds_read_b128 v[44:47], v52 offset:768
	v_xor_b32_e32 v39, 32, v235
	s_waitcnt lgkmcnt(0)
	v_fma_f32 v37, v44, v29, 0
	v_fmac_f32_e32 v37, v40, v30
	v_fmac_f32_e32 v37, v45, v31
	v_fmac_f32_e32 v37, v41, v32
	v_fmac_f32_e32 v37, v46, v33
	v_fmac_f32_e32 v37, v42, v34
	v_fmac_f32_e32 v37, v47, v35
	v_fmac_f32_e32 v37, v43, v36
	ds_read_b128 v[40:43], v52 offset:848
	ds_read_b128 v[44:47], v52 offset:832
	s_waitcnt lgkmcnt(0)
	v_fmac_f32_e32 v37, v44, v21
	v_fmac_f32_e32 v37, v40, v22
	v_fmac_f32_e32 v37, v45, v23
	v_fmac_f32_e32 v37, v41, v24
	v_fmac_f32_e32 v37, v46, v25
	v_fmac_f32_e32 v37, v42, v26
	v_fmac_f32_e32 v37, v47, v27
	v_fmac_f32_e32 v37, v43, v28
	ds_read_b128 v[40:43], v52 offset:912
	ds_read_b128 v[44:47], v52 offset:896
	s_waitcnt lgkmcnt(0)
	v_fmac_f32_e32 v37, v44, v17
	v_fmac_f32_e32 v37, v40, v18
	v_fmac_f32_e32 v37, v45, v19
	v_fmac_f32_e32 v37, v41, v20
	v_mov_b32_e32 v40, v42
	v_mov_b32_e32 v41, v46
	v_pk_mul_f32 v[40:41], v[40:41], v[14:15]
	v_mov_b32_e32 v46, v43
	v_add_f32_e32 v37, v41, v37
	v_add_f32_e32 v37, v40, v37
	v_pk_mul_f32 v[40:41], v[46:47], v[12:13]
	s_nop 0
	v_add_f32_e32 v37, v41, v37
	v_add_f32_e32 v37, v40, v37
	ds_read_b128 v[40:43], v52 offset:976
	ds_read_b128 v[44:47], v52 offset:960
	s_waitcnt lgkmcnt(1)
	v_mov_b32_e32 v48, v40
	s_waitcnt lgkmcnt(0)
	v_mov_b32_e32 v49, v44
	v_pk_mul_f32 v[48:49], v[48:49], v[10:11]
	v_mov_b32_e32 v44, v41
	v_add_f32_e32 v37, v49, v37
	v_add_f32_e32 v37, v48, v37
	v_pk_mul_f32 v[40:41], v[44:45], v[8:9]
	s_nop 0
	v_add_f32_e32 v37, v41, v37
	v_add_f32_e32 v37, v40, v37
	v_mov_b32_e32 v40, v42
	v_mov_b32_e32 v41, v46
	v_pk_mul_f32 v[40:41], v[40:41], v[6:7]
	v_mov_b32_e32 v46, v43
	v_add_f32_e32 v37, v41, v37
	v_add_f32_e32 v37, v40, v37
	v_pk_mul_f32 v[40:41], v[46:47], v[4:5]
	s_nop 0
	v_add_f32_e32 v37, v41, v37
	v_add_f32_e32 v37, v40, v37
	v_and_b32_e32 v40, 64, v235
	v_add_u32_e32 v40, 64, v40
	v_cmp_lt_i32_e32 vcc, v39, v40
	s_nop 1
	v_cndmask_b32_e32 v39, v235, v39, vcc
	v_lshlrev_b32_e32 v39, 2, v39
	ds_bpermute_b32 v39, v39, v37
	s_waitcnt lgkmcnt(0)
	v_add_f32_e32 v37, v37, v39
.LBB0_1509:
	s_cmp_gt_u32 s42, 39
	v_mov_b32_e32 v39, 0
	s_cselect_b64 s[24:25], -1, 0
	s_cmp_lt_u32 s42, 40
	v_mov_b32_e32 v40, 0
	s_cbranch_scc1 .LBB0_1511
	ds_read_b128 v[40:43], v52 offset:1040
	ds_read_b128 v[44:47], v52 offset:1024
	s_waitcnt lgkmcnt(0)
	v_fma_f32 v48, v44, v29, 0
	v_fmac_f32_e32 v48, v40, v30
	v_fmac_f32_e32 v48, v45, v31
	v_fmac_f32_e32 v48, v41, v32
	v_fmac_f32_e32 v48, v46, v33
	v_fmac_f32_e32 v48, v42, v34
	v_fmac_f32_e32 v48, v47, v35
	v_fmac_f32_e32 v48, v43, v36
	ds_read_b128 v[40:43], v52 offset:1104
	ds_read_b128 v[44:47], v52 offset:1088
	s_waitcnt lgkmcnt(0)
	v_fmac_f32_e32 v48, v44, v21
	v_fmac_f32_e32 v48, v40, v22
	v_fmac_f32_e32 v48, v45, v23
	v_fmac_f32_e32 v48, v41, v24
	v_fmac_f32_e32 v48, v46, v25
	v_fmac_f32_e32 v48, v42, v26
	v_fmac_f32_e32 v48, v47, v27
	v_fmac_f32_e32 v48, v43, v28
	ds_read_b128 v[40:43], v52 offset:1168
	ds_read_b128 v[44:47], v52 offset:1152
	s_waitcnt lgkmcnt(0)
	v_fmac_f32_e32 v48, v44, v17
	v_fmac_f32_e32 v48, v40, v18
	v_fmac_f32_e32 v48, v45, v19
	v_fmac_f32_e32 v48, v41, v20
	v_mov_b32_e32 v40, v42
	v_mov_b32_e32 v41, v46
	v_pk_mul_f32 v[40:41], v[40:41], v[14:15]
	v_mov_b32_e32 v46, v43
	v_add_f32_e32 v41, v41, v48
	v_add_f32_e32 v42, v40, v41
	v_pk_mul_f32 v[40:41], v[46:47], v[12:13]
	s_nop 0
	v_add_f32_e32 v41, v41, v42
	v_add_f32_e32 v50, v40, v41
	ds_read_b128 v[40:43], v52 offset:1232
	ds_read_b128 v[44:47], v52 offset:1216
	s_waitcnt lgkmcnt(1)
	v_mov_b32_e32 v48, v40
	s_waitcnt lgkmcnt(0)
	v_mov_b32_e32 v49, v44
	v_pk_mul_f32 v[48:49], v[48:49], v[10:11]
	v_mov_b32_e32 v44, v41
	v_add_f32_e32 v40, v49, v50
	v_add_f32_e32 v48, v48, v40
	v_pk_mul_f32 v[40:41], v[44:45], v[8:9]
	s_nop 0
	v_add_f32_e32 v41, v41, v48
	v_add_f32_e32 v44, v40, v41
	v_mov_b32_e32 v40, v42
	v_mov_b32_e32 v41, v46
	v_pk_mul_f32 v[40:41], v[40:41], v[6:7]
	v_mov_b32_e32 v46, v43
	v_add_f32_e32 v41, v41, v44
	v_add_f32_e32 v42, v40, v41
	v_pk_mul_f32 v[40:41], v[46:47], v[4:5]
	s_nop 0
	v_add_f32_e32 v41, v41, v42
	v_and_b32_e32 v42, 64, v235
	v_add_f32_e32 v40, v40, v41
	v_xor_b32_e32 v41, 32, v235
	v_add_u32_e32 v42, 64, v42
	v_cmp_lt_i32_e32 vcc, v41, v42
	s_nop 1
	v_cndmask_b32_e32 v41, v235, v41, vcc
	v_lshlrev_b32_e32 v41, 2, v41
	ds_bpermute_b32 v41, v41, v40
	s_waitcnt lgkmcnt(0)
	v_add_f32_e32 v40, v40, v41
.LBB0_1511:
	s_cmp_gt_u32 s42, 47
	s_cselect_b64 s[26:27], -1, 0
	s_cmp_lt_u32 s42, 48
	s_cbranch_scc1 .LBB0_1513
	ds_read_b128 v[42:45], v52 offset:1296
	ds_read_b128 v[46:49], v52 offset:1280
	v_xor_b32_e32 v41, 32, v235
	s_waitcnt lgkmcnt(0)
	v_fma_f32 v39, v46, v29, 0
	v_fmac_f32_e32 v39, v42, v30
	v_fmac_f32_e32 v39, v47, v31
	v_fmac_f32_e32 v39, v43, v32
	v_fmac_f32_e32 v39, v48, v33
	v_fmac_f32_e32 v39, v44, v34
	v_fmac_f32_e32 v39, v49, v35
	v_fmac_f32_e32 v39, v45, v36
	ds_read_b128 v[42:45], v52 offset:1360
	ds_read_b128 v[46:49], v52 offset:1344
	s_waitcnt lgkmcnt(0)
	v_fmac_f32_e32 v39, v46, v21
	v_fmac_f32_e32 v39, v42, v22
	v_fmac_f32_e32 v39, v47, v23
	v_fmac_f32_e32 v39, v43, v24
	v_fmac_f32_e32 v39, v48, v25
	v_fmac_f32_e32 v39, v44, v26
	v_fmac_f32_e32 v39, v49, v27
	v_fmac_f32_e32 v39, v45, v28
	ds_read_b128 v[42:45], v52 offset:1424
	ds_read_b128 v[46:49], v52 offset:1408
	s_waitcnt lgkmcnt(0)
	v_fmac_f32_e32 v39, v46, v17
	v_fmac_f32_e32 v39, v42, v18
	v_fmac_f32_e32 v39, v47, v19
	v_fmac_f32_e32 v39, v43, v20
	v_mov_b32_e32 v42, v44
	v_mov_b32_e32 v43, v48
	v_pk_mul_f32 v[42:43], v[42:43], v[14:15]
	v_mov_b32_e32 v48, v45
	v_add_f32_e32 v39, v43, v39
	v_add_f32_e32 v39, v42, v39
	v_pk_mul_f32 v[42:43], v[48:49], v[12:13]
	s_nop 0
	v_add_f32_e32 v39, v43, v39
	v_add_f32_e32 v39, v42, v39
	ds_read_b128 v[42:45], v52 offset:1488
	ds_read_b128 v[46:49], v52 offset:1472
	s_waitcnt lgkmcnt(1)
	v_mov_b32_e32 v50, v42
	s_waitcnt lgkmcnt(0)
	v_mov_b32_e32 v51, v46
	v_pk_mul_f32 v[50:51], v[50:51], v[10:11]
	v_mov_b32_e32 v46, v43
	v_add_f32_e32 v39, v51, v39
	v_add_f32_e32 v39, v50, v39
	v_pk_mul_f32 v[42:43], v[46:47], v[8:9]
	s_nop 0
	v_add_f32_e32 v39, v43, v39
	v_add_f32_e32 v39, v42, v39
	v_mov_b32_e32 v42, v44
	v_mov_b32_e32 v43, v48
	v_pk_mul_f32 v[42:43], v[42:43], v[6:7]
	v_mov_b32_e32 v48, v45
	v_add_f32_e32 v39, v43, v39
	v_add_f32_e32 v39, v42, v39
	v_pk_mul_f32 v[42:43], v[48:49], v[4:5]
	s_nop 0
	v_add_f32_e32 v39, v43, v39
	v_add_f32_e32 v39, v42, v39
	v_and_b32_e32 v42, 64, v235
	v_add_u32_e32 v42, 64, v42
	v_cmp_lt_i32_e32 vcc, v41, v42
	s_nop 1
	v_cndmask_b32_e32 v41, v235, v41, vcc
	v_lshlrev_b32_e32 v41, 2, v41
	ds_bpermute_b32 v41, v41, v39
	s_waitcnt lgkmcnt(0)
	v_add_f32_e32 v39, v39, v41
.LBB0_1513:
	s_lshr_b32 s19, s42, 3
	s_cmp_eq_u32 s19, 7
	s_cselect_b64 s[4:5], -1, 0
	s_cmp_lg_u32 s19, 7
	v_mov_b32_e32 v41, 0
	s_cbranch_scc1 .LBB0_1515
	ds_read_b128 v[42:45], v52 offset:1552
	ds_read_b128 v[46:49], v52 offset:1536
	s_waitcnt lgkmcnt(0)
	v_fma_f32 v41, v46, v29, 0
	v_fmac_f32_e32 v41, v42, v30
	v_fmac_f32_e32 v41, v47, v31
	v_fmac_f32_e32 v41, v43, v32
	v_fmac_f32_e32 v41, v48, v33
	v_fmac_f32_e32 v41, v44, v34
	v_fmac_f32_e32 v41, v49, v35
	v_fmac_f32_e32 v41, v45, v36
	ds_read_b128 v[30:33], v52 offset:1616
	ds_read_b128 v[42:45], v52 offset:1600
	s_waitcnt lgkmcnt(0)
	v_fmac_f32_e32 v41, v42, v21
	v_fmac_f32_e32 v41, v30, v22
	v_fmac_f32_e32 v41, v43, v23
	v_fmac_f32_e32 v41, v31, v24
	v_fmac_f32_e32 v41, v44, v25
	v_fmac_f32_e32 v41, v32, v26
	v_fmac_f32_e32 v41, v45, v27
	v_fmac_f32_e32 v41, v33, v28
	ds_read_b128 v[22:25], v52 offset:1680
	ds_read_b128 v[26:29], v52 offset:1664
	s_waitcnt lgkmcnt(0)
	v_fmac_f32_e32 v41, v26, v17
	v_fmac_f32_e32 v41, v22, v18
	v_fmac_f32_e32 v41, v27, v19
	v_mov_b32_e32 v18, v24
	v_mov_b32_e32 v19, v28
	v_fmac_f32_e32 v41, v23, v20
	v_pk_mul_f32 v[14:15], v[18:19], v[14:15]
	v_mov_b32_e32 v28, v25
	v_add_f32_e32 v15, v15, v41
	v_add_f32_e32 v14, v14, v15
	v_pk_mul_f32 v[12:13], v[28:29], v[12:13]
	s_nop 0
	v_add_f32_e32 v13, v13, v14
	v_add_f32_e32 v17, v12, v13
	ds_read_b128 v[12:15], v52 offset:1744
	ds_read_b128 v[18:21], v52 offset:1728
	s_waitcnt lgkmcnt(1)
	v_mov_b32_e32 v2, v12
	s_waitcnt lgkmcnt(0)
	v_mov_b32_e32 v3, v18
	v_pk_mul_f32 v[2:3], v[2:3], v[10:11]
	v_mov_b32_e32 v18, v13
	v_add_f32_e32 v3, v3, v17
	v_add_f32_e32 v10, v2, v3
	v_pk_mul_f32 v[2:3], v[18:19], v[8:9]
	s_nop 0
	v_add_f32_e32 v3, v3, v10
	v_add_f32_e32 v8, v2, v3
	v_mov_b32_e32 v2, v14
	v_mov_b32_e32 v3, v20
	v_pk_mul_f32 v[2:3], v[2:3], v[6:7]
	v_mov_b32_e32 v20, v15
	v_add_f32_e32 v3, v3, v8
	v_add_f32_e32 v6, v2, v3
	v_pk_mul_f32 v[2:3], v[20:21], v[4:5]
	v_and_b32_e32 v4, 64, v235
	v_add_f32_e32 v3, v3, v6
	v_add_f32_e32 v2, v2, v3
	v_xor_b32_e32 v3, 32, v235
	v_add_u32_e32 v4, 64, v4
	v_cmp_lt_i32_e32 vcc, v3, v4
	s_nop 1
	v_cndmask_b32_e32 v3, v235, v3, vcc
	v_lshlrev_b32_e32 v3, 2, v3
	ds_bpermute_b32 v3, v3, v2
	s_waitcnt lgkmcnt(0)
	v_add_f32_e32 v41, v2, v3
